# prompt attention: row max and rescale decision of a tile moved into the gaps of the first four PV MFMAs (four max chains), exps follow from the fifth gap
# baseline (speedup 1.0000x reference)
.Lat_t1:
	s_add_i32 s26, s24, 1
	s_and_b32 s26, s26, 3
	s_lshl_b32 s26, s26, 13
	s_lshl_b32 s27, s24, 13
	s_add_i32 s28, s24, 3
	s_and_b32 s28, s28, 3
	s_lshl_b32 s28, s28, 14
	s_add_i32 s28, s28, 0x8000
	s_add_i32 s29, s24, 2
	s_and_b32 s29, s29, 3
	s_lshl_b32 s29, s29, 14
	s_add_i32 s29, s29, 0x8000
	s_cmp_lt_u32 s17, s16
	s_cbranch_scc0 .Lat_last4
	s_cmp_eq_u32 s17, 0
	s_cbranch_scc1 .Lat_first3
	v_add_u32_e32 v218, s28, v229
	ds_read_b64_tr_b16 v[116:117], v218 offset:0
	ds_read_b64_tr_b16 v[118:119], v218 offset:512
	v_mfma_f32_32x32x16_bf16 v[52:67], v[20:23], v[4:7], v[84:99]
	ds_read_b64_tr_b16 v[120:121], v218 offset:4096
	ds_read_b64_tr_b16 v[122:123], v218 offset:4608
	v_mfma_f32_32x32x16_bf16 v[52:67], v[24:27], v[8:11], v[52:67]
	ds_read_b64_tr_b16 v[124:125], v218 offset:8192
	ds_read_b64_tr_b16 v[126:127], v218 offset:8704
	v_mfma_f32_32x32x16_bf16 v[52:67], v[28:31], v[12:15], v[52:67]
	ds_read_b64_tr_b16 v[128:129], v218 offset:12288
	ds_read_b64_tr_b16 v[130:131], v218 offset:12800
	v_mfma_f32_32x32x16_bf16 v[52:67], v[32:35], v[16:19], v[52:67]
	ds_read_b64_tr_b16 v[132:133], v218 offset:1024
	ds_read_b64_tr_b16 v[134:135], v218 offset:1536
	v_mfma_f32_32x32x16_bf16 v[68:83], v[36:39], v[4:7], v[84:99]
	ds_read_b64_tr_b16 v[136:137], v218 offset:5120
	ds_read_b64_tr_b16 v[138:139], v218 offset:5632
	v_mfma_f32_32x32x16_bf16 v[68:83], v[40:43], v[8:11], v[68:83]
	ds_read_b64_tr_b16 v[140:141], v218 offset:9216
	ds_read_b64_tr_b16 v[142:143], v218 offset:9728
	v_mfma_f32_32x32x16_bf16 v[68:83], v[44:47], v[12:15], v[68:83]
	ds_read_b64_tr_b16 v[144:145], v218 offset:13312
	ds_read_b64_tr_b16 v[146:147], v218 offset:13824
	v_mfma_f32_32x32x16_bf16 v[68:83], v[48:51], v[16:19], v[68:83]
	s_waitcnt lgkmcnt(0)
	v_mfma_f32_32x32x16_bf16 v[148:163], v[100:103], v[116:119], v[148:163]
	v_max3_f32 v219, v52, v53, v54
	v_max3_f32 v220, v55, v56, v57
	v_max3_f32 v221, v58, v59, v60
	v_max3_f32 v223, v61, v62, v63
	v_max3_f32 v219, v219, v64, v65
	ds_read_b64_tr_b16 v[116:117], v218 offset:2048
	ds_read_b64_tr_b16 v[118:119], v218 offset:2560
	v_mfma_f32_32x32x16_bf16 v[164:179], v[100:103], v[120:123], v[164:179]
	v_max3_f32 v220, v220, v66, v67
	v_max3_f32 v221, v221, v68, v69
	v_max3_f32 v223, v223, v70, v71
	v_max3_f32 v219, v219, v72, v73
	v_max3_f32 v220, v220, v74, v75
	ds_read_b64_tr_b16 v[120:121], v218 offset:6144
	ds_read_b64_tr_b16 v[122:123], v218 offset:6656
	v_mfma_f32_32x32x16_bf16 v[180:195], v[100:103], v[124:127], v[180:195]
	v_max3_f32 v221, v221, v76, v77
	v_max3_f32 v223, v223, v78, v79
	v_max3_f32 v219, v219, v80, v81
	v_max3_f32 v220, v220, v82, v83
	v_max3_f32 v219, v219, v220, v221
	ds_read_b64_tr_b16 v[124:125], v218 offset:10240
	ds_read_b64_tr_b16 v[126:127], v218 offset:10752
	v_mfma_f32_32x32x16_bf16 v[196:211], v[100:103], v[128:131], v[196:211]
	v_max_f32_e32 v214, v219, v223
	v_mov_b32_e32 v219, v214
	s_nop 1
	v_permlane32_swap_b32_e32 v214, v219
	v_max_f32_e32 v214, v214, v219
	v_cmp_lt_f32_e32 vcc, s48, v214
	ds_read_b64_tr_b16 v[128:129], v218 offset:14336
	ds_read_b64_tr_b16 v[130:131], v218 offset:14848
	s_mov_b32 s54, 0
	s_cmp_lg_u64 vcc, 0
	s_cbranch_scc0 .Lat_nores6
	v_max_f32_e32 v214, 0, v214
	v_add_f32_e32 v212, v212, v214
	v_sub_f32_e32 v52, v52, v214
	v_sub_f32_e32 v53, v53, v214
	v_sub_f32_e32 v54, v54, v214
	v_sub_f32_e32 v55, v55, v214
	v_sub_f32_e32 v56, v56, v214
	v_sub_f32_e32 v57, v57, v214
	v_sub_f32_e32 v58, v58, v214
	v_sub_f32_e32 v59, v59, v214
	v_sub_f32_e32 v60, v60, v214
	v_sub_f32_e32 v61, v61, v214
	v_sub_f32_e32 v62, v62, v214
	v_sub_f32_e32 v63, v63, v214
	v_sub_f32_e32 v64, v64, v214
	v_sub_f32_e32 v65, v65, v214
	v_sub_f32_e32 v66, v66, v214
	v_sub_f32_e32 v67, v67, v214
	v_sub_f32_e32 v68, v68, v214
	v_sub_f32_e32 v69, v69, v214
	v_sub_f32_e32 v70, v70, v214
	v_sub_f32_e32 v71, v71, v214
	v_sub_f32_e32 v72, v72, v214
	v_sub_f32_e32 v73, v73, v214
	v_sub_f32_e32 v74, v74, v214
	v_sub_f32_e32 v75, v75, v214
	v_sub_f32_e32 v76, v76, v214
	v_sub_f32_e32 v77, v77, v214
	v_sub_f32_e32 v78, v78, v214
	v_sub_f32_e32 v79, v79, v214
	v_sub_f32_e32 v80, v80, v214
	v_sub_f32_e32 v81, v81, v214
	v_sub_f32_e32 v82, v82, v214
	v_sub_f32_e32 v83, v83, v214
	v_xor_b32_e32 v84, 0x80000000, v212
	v_xor_b32_e32 v85, 0x80000000, v212
	v_xor_b32_e32 v86, 0x80000000, v212
	v_xor_b32_e32 v87, 0x80000000, v212
	v_xor_b32_e32 v88, 0x80000000, v212
	v_xor_b32_e32 v89, 0x80000000, v212
	v_xor_b32_e32 v90, 0x80000000, v212
	v_xor_b32_e32 v91, 0x80000000, v212
	v_xor_b32_e32 v92, 0x80000000, v212
	v_xor_b32_e32 v93, 0x80000000, v212
	v_xor_b32_e32 v94, 0x80000000, v212
	v_xor_b32_e32 v95, 0x80000000, v212
	v_xor_b32_e32 v96, 0x80000000, v212
	v_xor_b32_e32 v97, 0x80000000, v212
	v_xor_b32_e32 v98, 0x80000000, v212
	v_xor_b32_e32 v99, 0x80000000, v212
	v_exp_f32_e64 v215, -v214
	s_mov_b32 s54, 1
	v_add_u32_e32 v222, v230, v240
	v_mul_f32_e32 v213, v213, v215
	ds_write_b32 v222, v215 offset:0
.Lat_nores6:
	v_mfma_f32_32x32x16_bf16 v[148:163], v[104:107], v[132:135], v[148:163]
	v_exp_f32_e32 v52, v52
	v_exp_f32_e32 v53, v53
	v_exp_f32_e32 v54, v54
	ds_read_b64_tr_b16 v[132:133], v218 offset:3072
	ds_read_b64_tr_b16 v[134:135], v218 offset:3584
	v_mfma_f32_32x32x16_bf16 v[164:179], v[104:107], v[136:139], v[164:179]
	v_exp_f32_e32 v55, v55
	v_exp_f32_e32 v56, v56
	v_exp_f32_e32 v57, v57
	ds_read_b64_tr_b16 v[136:137], v218 offset:7168
	ds_read_b64_tr_b16 v[138:139], v218 offset:7680
	v_add_f32_e32 v216, v52, v53
	v_add_f32_e32 v216, v216, v54
	v_mfma_f32_32x32x16_bf16 v[180:195], v[104:107], v[140:143], v[180:195]
	v_exp_f32_e32 v58, v58
	v_exp_f32_e32 v59, v59
	v_exp_f32_e32 v60, v60
	ds_read_b64_tr_b16 v[140:141], v218 offset:11264
	ds_read_b64_tr_b16 v[142:143], v218 offset:11776
	v_add_f32_e32 v216, v216, v55
	v_add_f32_e32 v216, v216, v56
	v_add_f32_e32 v216, v216, v57
	v_mfma_f32_32x32x16_bf16 v[196:211], v[104:107], v[144:147], v[196:211]
	v_exp_f32_e32 v61, v61
	v_exp_f32_e32 v62, v62
	v_exp_f32_e32 v63, v63
	ds_read_b64_tr_b16 v[144:145], v218 offset:15360
	ds_read_b64_tr_b16 v[146:147], v218 offset:15872
	v_add_f32_e32 v216, v216, v58
	v_add_f32_e32 v216, v216, v59
	v_add_f32_e32 v216, v216, v60
	v_cvt_pk_bf16_f32 v100, v52, v53
	v_cvt_pk_bf16_f32 v101, v54, v55
	v_cvt_pk_bf16_f32 v102, v56, v57
	v_cvt_pk_bf16_f32 v103, v58, v59
	s_waitcnt lgkmcnt(14)
	v_mfma_f32_32x32x16_bf16 v[148:163], v[108:111], v[116:119], v[148:163]
	v_exp_f32_e32 v64, v64
	v_exp_f32_e32 v65, v65
	v_exp_f32_e32 v66, v66
	v_add_u32_e32 v225, s26, v235
	ds_read_b128 v[20:23], v225
	v_add_f32_e32 v216, v216, v61
	v_add_f32_e32 v216, v216, v62
	v_add_f32_e32 v216, v216, v63
	s_waitcnt lgkmcnt(13)
	v_mfma_f32_32x32x16_bf16 v[164:179], v[108:111], v[120:123], v[164:179]
	v_exp_f32_e32 v67, v67
	v_exp_f32_e32 v68, v68
	v_exp_f32_e32 v69, v69
	v_add_u32_e32 v226, s26, v236
	ds_read_b128 v[24:27], v226
	v_add_f32_e32 v216, v216, v64
	v_add_f32_e32 v216, v216, v65
	v_add_f32_e32 v216, v216, v66
	s_waitcnt lgkmcnt(12)
	v_mfma_f32_32x32x16_bf16 v[180:195], v[108:111], v[124:127], v[180:195]
	v_exp_f32_e32 v70, v70
	v_exp_f32_e32 v71, v71
	v_exp_f32_e32 v72, v72
	v_add_u32_e32 v227, s26, v237
	ds_read_b128 v[28:31], v227
	v_add_f32_e32 v216, v216, v67
	v_add_f32_e32 v216, v216, v68
	v_add_f32_e32 v216, v216, v69
	v_cvt_pk_bf16_f32 v104, v60, v61
	v_cvt_pk_bf16_f32 v105, v62, v63
	v_cvt_pk_bf16_f32 v106, v64, v65
	v_cvt_pk_bf16_f32 v107, v66, v67
	s_waitcnt lgkmcnt(11)
	v_mfma_f32_32x32x16_bf16 v[196:211], v[108:111], v[128:131], v[196:211]
	v_exp_f32_e32 v73, v73
	v_exp_f32_e32 v74, v74
	v_exp_f32_e32 v75, v75
	v_add_u32_e32 v228, s26, v238
	ds_read_b128 v[32:35], v228
	v_add_f32_e32 v216, v216, v70
	v_add_f32_e32 v216, v216, v71
	v_add_f32_e32 v216, v216, v72
	s_waitcnt lgkmcnt(10)
	v_mfma_f32_32x32x16_bf16 v[148:163], v[112:115], v[132:135], v[148:163]
	v_exp_f32_e32 v76, v76
	v_exp_f32_e32 v77, v77
	ds_read_b128 v[36:39], v225 offset:4096
	v_add_f32_e32 v216, v216, v73
	v_add_f32_e32 v216, v216, v74
	v_add_f32_e32 v216, v216, v75
	v_cvt_pk_bf16_f32 v108, v68, v69
	v_cvt_pk_bf16_f32 v109, v70, v71
	v_cvt_pk_bf16_f32 v110, v72, v73
	v_cvt_pk_bf16_f32 v111, v74, v75
	s_waitcnt lgkmcnt(9)
	v_mfma_f32_32x32x16_bf16 v[164:179], v[112:115], v[136:139], v[164:179]
	v_exp_f32_e32 v78, v78
	v_exp_f32_e32 v79, v79
	ds_read_b128 v[40:43], v226 offset:4096
	v_add_f32_e32 v216, v216, v76
	v_add_f32_e32 v216, v216, v77
	s_waitcnt lgkmcnt(8)
	v_mfma_f32_32x32x16_bf16 v[180:195], v[112:115], v[140:143], v[180:195]
	v_exp_f32_e32 v80, v80
	v_exp_f32_e32 v81, v81
	ds_read_b128 v[44:47], v227 offset:4096
	v_add_f32_e32 v216, v216, v78
	v_add_f32_e32 v216, v216, v79
	s_waitcnt lgkmcnt(7)
	v_mfma_f32_32x32x16_bf16 v[196:211], v[112:115], v[144:147], v[196:211]
	v_exp_f32_e32 v82, v82
	v_exp_f32_e32 v83, v83
	ds_read_b128 v[48:51], v228 offset:4096
	v_add_f32_e32 v216, v216, v80
	v_add_f32_e32 v216, v216, v81
	v_add_f32_e32 v216, v216, v82
	v_add_f32_e32 v216, v216, v83
	v_cvt_pk_bf16_f32 v112, v76, v77
	v_cvt_pk_bf16_f32 v113, v78, v79
	v_cvt_pk_bf16_f32 v114, v80, v81
	v_cvt_pk_bf16_f32 v115, v82, v83
	v_add_f32_e32 v213, v213, v216
	s_branch .Lat_end5
